# retention and SSD prompt items: waves 4-7 take mirrored causal row-tile roles so each SIMD pair holds one heavy and one light wave
# speedup vs baseline: 1.0058x; 1.0058x over previous
; DI f32x16 zero16() { f32x16 v; _Pragma("unroll") for (int i = 0; i < 16; ++i) v[i] = 0.f; return v; }
; DI int otid() { int t = threadIdx.x; asm volatile("" : "+v"(t)); return t; }
; template <class T> DI T* optr(T* p) { unsigned long long v = (unsigned long long)p; asm volatile("" : "+s"(v)); return (T*)(GAS T*)v; }
; DI void ret_prompt_item(char* shm, const Params& P, int l, int hf, int b, int hd) {
;   u16* QQ = (u16*)shm;
;   u16* KK = QQ + 128 * 72;
;   u16* KKt = KK + 128 * 72;
;   u16* Vt = KKt + 64 * 136;
;   u16* St = Vt + 128 * 136;
;   float* th = (float*)(St + 128 * 72);
;   u16* Z = (u16*)(optr(P.ws) + WS_Z);
;   const int tid = otid(), lane = tid & 63, w = tid >> 6, r = lane & 31, hh = lane >> 5;
;   const float log2g = log2f(1.f - exp2f(-5.f - (float)hd));
;   const float g128 = exp2f(log2g * 128.f);
;   __syncthreads();
;   for (int e = tid; e < 128 * 72; e += NT) St[e] = 0;
;   if (tid < 32) th[tid] = 1.f / powf(10000.f, (float)tid / 31.f);
;   f32x16 Sacc = zero16();
;   const int lt = w & 3, eh = w >> 2;
.LBB0_224:
	s_andn2_b64 vcc, exec, s[0:1]
	s_cbranch_vccnz .LBB0_239
	s_and_b32 s46, s97, 7
	v_cvt_f32_ubyte0_e32 v0, s46
	v_sub_f32_e32 v0, 0xc0a00000, v0
	s_mov_b32 s3, 0xc2fc0000
	v_cmp_gt_f32_e32 vcc, s3, v0
	s_and_b64 s[0:1], vcc, exec
	s_cselect_b32 s0, 0xffffffc0, 0
	s_waitcnt lgkmcnt(0)
	v_cndmask_b32_e32 v1, 0, v226, vcc
	v_add_f32_e32 v0, v0, v1
	v_exp_f32_e32 v0, v0
	v_mov_b32_e32 v1, 0x42000000
	s_mov_b64 s[4:5], s[74:75]
	v_ldexp_f32 v0, v0, s0
	v_sub_f32_e32 v0, 1.0, v0
	v_cmp_gt_f32_e32 vcc, s56, v0
	s_and_b64 s[0:1], vcc, exec
	s_cselect_b32 s0, 32, 0
	v_ldexp_f32 v0, v0, s0
	v_log_f32_e32 v0, v0
	v_cndmask_b32_e32 v2, 0, v1, vcc
	v_bfe_u32 v1, v242, 8, 1
	v_mul_u32_u24_e32 v1, 0xc0, v1
	v_xor_b32_e32 v1, v242, v1
	v_sub_f32_e32 v2, v0, v2
	v_mul_f32_e32 v0, 0x43000000, v2
	v_cmp_gt_f32_e32 vcc, s3, v0
	s_and_b64 s[0:1], vcc, exec
	s_movk_i32 s0, 0x2400
	s_cselect_b32 s10, 0xffffffc0, 0
	v_cmp_gt_i32_e64 s[0:1], s0, v1
	s_barrier
	s_and_saveexec_b64 s[6:7], s[0:1]
	s_cbranch_execz .LBB0_228
	v_readlane_b32 s0, v254, 8
	v_add_u32_e32 v0, 0xfffffe00, v1
	s_mov_b64 s[8:9], 0
	v_lshl_add_u32 v3, v1, 1, s0

; DI f32x16 zero16() { f32x16 v; _Pragma("unroll") for (int i = 0; i < 16; ++i) v[i] = 0.f; return v; }
; DI int otid() { int t = threadIdx.x; asm volatile("" : "+v"(t)); return t; }
; template <class T> DI T* optr(T* p) { unsigned long long v = (unsigned long long)p; asm volatile("" : "+s"(v)); return (T*)(GAS T*)v; }
; DI void ssd_prompt_item(char* shm, const Params& P, int l, int hf, int b, int hc) {
;   u16* Bm = (u16*)shm;
;   u16* Cm = Bm + 128 * 136;
;   u16* Xs = Cm + 128 * 136;
;   u16* XwT = Xs + 64 * 136;
;   u16* Hs = XwT + 64 * 136;
;   float* acum = (float*)(Hs + 64 * 136);
;   float* dtv = acum + 128;
;   float* tot = dtv + 128;
;   const u16* Z = (const u16*)(optr(P.ws) + WS_Z);
;   u16* YC = (u16*)(optr(P.ws) + WS_YC);
;   const u16* XBC = (const u16*)(optr(P.ws) + WS_XBC);
;   const float* DT = (const float*)(optr(P.ws) + WS_DT);
;   const int tid = otid(), lane = tid & 63, w = tid >> 6, r = lane & 31, hh = lane >> 5;
;   const int g = hc >> 3;
;   const float Aneg = -expf(P.A_log[l * 16 + hc]), dtb = P.dt_bias[l * 16 + hc], dsk = P.D_skip[l * 16 + hc];
;   const float* cw = P.conv_w + (size_t)l * 4 * 1536;
;   const float* cb = P.conv_b + (size_t)l * 1536;
;   const int lrowb = b * 2048 - hf * HALF_ROWS;
;   __syncthreads();
;   for (int e = tid; e < 64 * 136; e += NT) Hs[e] = 0;
;   f32x16 Hacc = zero16();
;   const int pt = w >> 2, it = w & 3;
.LBB0_240:
	s_andn2_b64 vcc, exec, s[0:1]
	s_cbranch_vccnz .LBB0_62
	s_and_b32 s84, s97, 15
	s_or_b32 s0, s84, s83
	s_lshl_b32 s0, s0, 2
	v_readlane_b32 s12, v254, 33
	s_mov_b64 s[56:57], s[74:75]
	s_mov_b64 s[6:7], s[74:75]
	s_mov_b64 s[10:11], s[74:75]
	s_mov_b64 s[8:9], s[74:75]
	v_bfe_u32 v122, v242, 8, 1
	v_mul_u32_u24_e32 v122, 0xc0, v122
	v_xor_b32_e32 v122, v242, v122
	s_waitcnt lgkmcnt(0)
	v_mov_b32_e32 v1, s0
	v_readlane_b32 s18, v254, 39
	v_readlane_b32 s19, v254, 40
	v_readlane_b32 s20, v254, 41
	v_readlane_b32 s21, v254, 42
	s_nop 2
	global_load_dword v0, v1, s[18:19]
	s_nop 0
	global_load_dword v124, v1, s[20:21]
	s_mov_b32 s0, 0xc2ce8ed0
	s_movk_i32 s3, 0x2200
	v_readlane_b32 s13, v254, 34
	v_cmp_gt_i32_e64 s[4:5], s3, v122
	v_readlane_b32 s14, v254, 35
	v_readlane_b32 s15, v254, 36
	v_readlane_b32 s16, v254, 37
	v_readlane_b32 s17, v254, 38
	v_readlane_b32 s22, v254, 43
	v_readlane_b32 s23, v254, 44
	v_readlane_b32 s24, v254, 45
	v_readlane_b32 s25, v254, 46
	v_readlane_b32 s26, v254, 47
	v_readlane_b32 s27, v254, 48
	s_barrier
	s_waitcnt vmcnt(1)
	v_cmp_ngt_f32_e32 vcc, s0, v0
	s_mov_b32 s0, 0x42b17218
	v_cmp_nlt_f32_e64 s[0:1], s0, v0
	s_and_saveexec_b64 s[12:13], s[4:5]
	s_cbranch_execz .LBB0_244
	v_readlane_b32 s3, v254, 10
	v_add_u32_e32 v1, 0xfffffe00, v122
	s_mov_b64 s[14:15], 0
	v_lshl_add_u32 v2, v122, 1, s3
